# scan pass 2 chunk-carry composition loop: 16 loads of a 4-entry trip issued back to back, composed in order
# speedup vs baseline: 1.0111x; 1.0029x over previous
.LBB0_1519:
	v_add_u32_e32 v31, 4, v31
	v_cmp_ge_i32_e32 vcc, v31, v30
	s_mov_b32 s2, 0xffeffff0
	s_mov_b32 s3, -1
	s_or_b64 s[12:13], vcc, s[12:13]
	s_mov_b64 vcc, 0x1000
	s_nop 0
	v_lshl_add_u64 v[144:145], v[28:29], 0, vcc
	v_lshl_add_u64 v[146:147], v[144:145], 0, vcc
	v_lshl_add_u64 v[148:149], v[146:147], 0, vcc
	v_lshl_add_u64 v[150:151], v[28:29], 0, s[2:3]
	v_lshl_add_u64 v[152:153], v[144:145], 0, s[2:3]
	v_lshl_add_u64 v[154:155], v[146:147], 0, s[2:3]
	v_lshl_add_u64 v[156:157], v[148:149], 0, s[2:3]
	global_load_dwordx4 v[80:83], v[150:151], off
	global_load_dwordx4 v[84:87], v[150:151], off offset:16
	global_load_dwordx4 v[88:91], v[28:29], off offset:-16
	global_load_dwordx4 v[92:95], v[28:29], off
	global_load_dwordx4 v[96:99], v[152:153], off
	global_load_dwordx4 v[100:103], v[152:153], off offset:16
	global_load_dwordx4 v[104:107], v[144:145], off offset:-16
	global_load_dwordx4 v[108:111], v[144:145], off
	global_load_dwordx4 v[112:115], v[154:155], off
	global_load_dwordx4 v[116:119], v[154:155], off offset:16
	global_load_dwordx4 v[120:123], v[146:147], off offset:-16
	global_load_dwordx4 v[124:127], v[146:147], off
	global_load_dwordx4 v[128:131], v[156:157], off
	global_load_dwordx4 v[132:135], v[156:157], off offset:16
	global_load_dwordx4 v[136:139], v[148:149], off offset:-16
	global_load_dwordx4 v[140:143], v[148:149], off
	v_lshl_add_u64 v[28:29], v[28:29], 0, s[46:47]
	s_waitcnt vmcnt(12)
	v_pk_fma_f32 v[0:1], v[80:81], v[0:1], v[88:89]
	v_pk_mul_f32 v[12:13], v[80:81], v[12:13]
	v_pk_fma_f32 v[2:3], v[82:83], v[2:3], v[90:91]
	v_pk_mul_f32 v[14:15], v[82:83], v[14:15]
	v_pk_fma_f32 v[4:5], v[84:85], v[4:5], v[92:93]
	v_pk_mul_f32 v[8:9], v[84:85], v[8:9]
	v_pk_fma_f32 v[6:7], v[86:87], v[6:7], v[94:95]
	v_pk_mul_f32 v[10:11], v[86:87], v[10:11]
	s_waitcnt vmcnt(8)
	v_pk_fma_f32 v[0:1], v[96:97], v[0:1], v[104:105]
	v_pk_mul_f32 v[12:13], v[96:97], v[12:13]
	v_pk_fma_f32 v[2:3], v[98:99], v[2:3], v[106:107]
	v_pk_mul_f32 v[14:15], v[98:99], v[14:15]
	v_pk_fma_f32 v[4:5], v[100:101], v[4:5], v[108:109]
	v_pk_mul_f32 v[8:9], v[100:101], v[8:9]
	v_pk_fma_f32 v[6:7], v[102:103], v[6:7], v[110:111]
	v_pk_mul_f32 v[10:11], v[102:103], v[10:11]
	s_waitcnt vmcnt(4)
	v_pk_fma_f32 v[0:1], v[112:113], v[0:1], v[120:121]
	v_pk_mul_f32 v[12:13], v[112:113], v[12:13]
	v_pk_fma_f32 v[2:3], v[114:115], v[2:3], v[122:123]
	v_pk_mul_f32 v[14:15], v[114:115], v[14:15]
	v_pk_fma_f32 v[4:5], v[116:117], v[4:5], v[124:125]
	v_pk_mul_f32 v[8:9], v[116:117], v[8:9]
	v_pk_fma_f32 v[6:7], v[118:119], v[6:7], v[126:127]
	v_pk_mul_f32 v[10:11], v[118:119], v[10:11]
	s_waitcnt vmcnt(0)
	v_pk_fma_f32 v[0:1], v[128:129], v[0:1], v[136:137]
	v_pk_mul_f32 v[12:13], v[128:129], v[12:13]
	v_pk_fma_f32 v[2:3], v[130:131], v[2:3], v[138:139]
	v_pk_mul_f32 v[14:15], v[130:131], v[14:15]
	v_pk_fma_f32 v[4:5], v[132:133], v[4:5], v[140:141]
	v_pk_mul_f32 v[8:9], v[132:133], v[8:9]
	v_pk_fma_f32 v[6:7], v[134:135], v[6:7], v[142:143]
	v_pk_mul_f32 v[10:11], v[134:135], v[10:11]
	s_andn2_b64 exec, exec, s[12:13]
	s_cbranch_execnz .LBB0_1519
	s_or_b64 exec, exec, s[12:13]
